# phase0 mod_partials: each (ks,cgp) item split over two waves on WGs 0..95 with LDS combine; layer-0 transposes on WGs 96..255
# speedup vs baseline: 1.0129x; 1.0129x over previous
.LBB0_17:
	v_mov_b32_e32 v16, v224
	s_lshl_b32 s72, s2, 3
	s_movk_i32 s0, 0x180
	s_cmpk_eq_i32 s26, 0x100
	s_cselect_b32 s0, 0x300, s0
	v_ashrrev_i32_e32 v6, 6, v16
	v_add_u32_e32 v17, s72, v6
	s_lshl_b32 s33, s26, 3
	v_mov_b32_e32 v0, v224
	v_cmp_gt_i32_e32 vcc, s0, v17
	v_mbcnt_lo_u32_b32 v225, -1, 0
	s_and_saveexec_b64 s[0:1], vcc
	s_cbranch_execz .LBB0_24
	s_cmpk_lg_i32 s26, 0x100
	s_cbranch_scc1 .Lmp_orig
	v_lshrrev_b32_e32 v1, 6, v16
	v_and_b32_e32 v27, 63, v16
	v_lshlrev_b32_e32 v27, 2, v27
	v_readfirstlane_b32 s3, v1
	s_nop 3
	s_and_b32 s4, s3, 3
	s_lshr_b32 s5, s3, 2
	s_and_b32 s6, s2, 1
	s_lshl_b32 s6, s6, 2
	s_add_i32 s4, s4, s6
	s_lshr_b32 s6, s2, 1
	s_lshl_b32 s7, s4, 7
	s_lshl_b32 s8, s5, 6
	s_add_i32 s7, s7, s8
	s_lshl_b32 s8, s7, 2
	s_waitcnt lgkmcnt(0)
	s_add_u32 s10, s48, s8
	s_addc_u32 s11, s49, 0
	global_load_dword v0, v27, s[10:11]
	s_add_u32 s10, s46, s8
	s_addc_u32 s11, s47, 0
	global_load_dword v23, v27, s[10:11]
	s_add_u32 s10, s10, 0x1000
	s_addc_u32 s11, s11, 0
	global_load_dword v24, v27, s[10:11]
	s_add_u32 s10, s10, 0x1000
	s_addc_u32 s11, s11, 0
	global_load_dword v25, v27, s[10:11]
	s_add_u32 s10, s10, 0x1000
	s_addc_u32 s11, s11, 0
	global_load_dword v26, v27, s[10:11]
	s_mul_i32 s8, s7, 0x3000
	s_lshl_b32 s9, s6, 8
	s_add_u32 s8, s8, s9
	s_add_u32 s98, s52, s8
	s_addc_u32 s99, s53, 0
	global_load_dword v132, v27, s[98:99] nt
	s_add_u32 s98, s98, 0x3000
	s_addc_u32 s99, s99, 0
	global_load_dword v133, v27, s[98:99] nt
	s_add_u32 s98, s98, 0x3000
	s_addc_u32 s99, s99, 0
	global_load_dword v134, v27, s[98:99] nt
	s_add_u32 s98, s98, 0x3000
	s_addc_u32 s99, s99, 0
	global_load_dword v135, v27, s[98:99] nt
	s_add_u32 s98, s98, 0x3000
	s_addc_u32 s99, s99, 0
	global_load_dword v136, v27, s[98:99] nt
	s_add_u32 s98, s98, 0x3000
	s_addc_u32 s99, s99, 0
	global_load_dword v137, v27, s[98:99] nt
	s_add_u32 s98, s98, 0x3000
	s_addc_u32 s99, s99, 0
	global_load_dword v138, v27, s[98:99] nt
	s_add_u32 s98, s98, 0x3000
	s_addc_u32 s99, s99, 0
	global_load_dword v139, v27, s[98:99] nt
	s_add_u32 s98, s98, 0x3000
	s_addc_u32 s99, s99, 0
	global_load_dword v140, v27, s[98:99] nt
	s_add_u32 s98, s98, 0x3000
	s_addc_u32 s99, s99, 0
	global_load_dword v141, v27, s[98:99] nt
	s_add_u32 s98, s98, 0x3000
	s_addc_u32 s99, s99, 0
	global_load_dword v142, v27, s[98:99] nt
	s_add_u32 s98, s98, 0x3000
	s_addc_u32 s99, s99, 0
	global_load_dword v143, v27, s[98:99] nt
	s_add_u32 s98, s98, 0x3000
	s_addc_u32 s99, s99, 0
	global_load_dword v144, v27, s[98:99] nt
	s_add_u32 s98, s98, 0x3000
	s_addc_u32 s99, s99, 0
	global_load_dword v145, v27, s[98:99] nt
	s_add_u32 s98, s98, 0x3000
	s_addc_u32 s99, s99, 0
	global_load_dword v146, v27, s[98:99] nt
	s_add_u32 s98, s98, 0x3000
	s_addc_u32 s99, s99, 0
	global_load_dword v147, v27, s[98:99] nt
	s_add_u32 s98, s98, 0x3000
	s_addc_u32 s99, s99, 0
	global_load_dword v148, v27, s[98:99] nt
	s_add_u32 s98, s98, 0x3000
	s_addc_u32 s99, s99, 0
	global_load_dword v149, v27, s[98:99] nt
	s_add_u32 s98, s98, 0x3000
	s_addc_u32 s99, s99, 0
	global_load_dword v150, v27, s[98:99] nt
	s_add_u32 s98, s98, 0x3000
	s_addc_u32 s99, s99, 0
	global_load_dword v151, v27, s[98:99] nt
	s_add_u32 s98, s98, 0x3000
	s_addc_u32 s99, s99, 0
	global_load_dword v152, v27, s[98:99] nt
	s_add_u32 s98, s98, 0x3000
	s_addc_u32 s99, s99, 0
	global_load_dword v153, v27, s[98:99] nt
	s_add_u32 s98, s98, 0x3000
	s_addc_u32 s99, s99, 0
	global_load_dword v154, v27, s[98:99] nt
	s_add_u32 s98, s98, 0x3000
	s_addc_u32 s99, s99, 0
	global_load_dword v155, v27, s[98:99] nt
	s_add_u32 s98, s98, 0x3000
	s_addc_u32 s99, s99, 0
	global_load_dword v156, v27, s[98:99] nt
	s_add_u32 s98, s98, 0x3000
	s_addc_u32 s99, s99, 0
	global_load_dword v157, v27, s[98:99] nt
	s_add_u32 s98, s98, 0x3000
	s_addc_u32 s99, s99, 0
	global_load_dword v158, v27, s[98:99] nt
	s_add_u32 s98, s98, 0x3000
	s_addc_u32 s99, s99, 0
	global_load_dword v159, v27, s[98:99] nt
	s_add_u32 s98, s98, 0x3000
	s_addc_u32 s99, s99, 0
	global_load_dword v160, v27, s[98:99] nt
	s_add_u32 s98, s98, 0x3000
	s_addc_u32 s99, s99, 0
	global_load_dword v161, v27, s[98:99] nt
	s_add_u32 s98, s98, 0x3000
	s_addc_u32 s99, s99, 0
	global_load_dword v162, v27, s[98:99] nt
	s_add_u32 s98, s98, 0x3000
	s_addc_u32 s99, s99, 0
	global_load_dword v163, v27, s[98:99] nt
	s_add_u32 s98, s98, 0x3000
	s_addc_u32 s99, s99, 0
	global_load_dword v164, v27, s[98:99] nt
	s_add_u32 s98, s98, 0x3000
	s_addc_u32 s99, s99, 0
	global_load_dword v165, v27, s[98:99] nt
	s_add_u32 s98, s98, 0x3000
	s_addc_u32 s99, s99, 0
	global_load_dword v166, v27, s[98:99] nt
	s_add_u32 s98, s98, 0x3000
	s_addc_u32 s99, s99, 0
	global_load_dword v167, v27, s[98:99] nt
	s_add_u32 s98, s98, 0x3000
	s_addc_u32 s99, s99, 0
	global_load_dword v168, v27, s[98:99] nt
	s_add_u32 s98, s98, 0x3000
	s_addc_u32 s99, s99, 0
	global_load_dword v169, v27, s[98:99] nt
	s_add_u32 s98, s98, 0x3000
	s_addc_u32 s99, s99, 0
	global_load_dword v170, v27, s[98:99] nt
	s_add_u32 s98, s98, 0x3000
	s_addc_u32 s99, s99, 0
	global_load_dword v171, v27, s[98:99] nt
	s_add_u32 s98, s98, 0x3000
	s_addc_u32 s99, s99, 0
	global_load_dword v172, v27, s[98:99] nt
	s_add_u32 s98, s98, 0x3000
	s_addc_u32 s99, s99, 0
	global_load_dword v173, v27, s[98:99] nt
	s_add_u32 s98, s98, 0x3000
	s_addc_u32 s99, s99, 0
	global_load_dword v174, v27, s[98:99] nt
	s_add_u32 s98, s98, 0x3000
	s_addc_u32 s99, s99, 0
	global_load_dword v175, v27, s[98:99] nt
	s_add_u32 s98, s98, 0x3000
	s_addc_u32 s99, s99, 0
	global_load_dword v176, v27, s[98:99] nt
	s_add_u32 s98, s98, 0x3000
	s_addc_u32 s99, s99, 0
	global_load_dword v177, v27, s[98:99] nt
	s_add_u32 s98, s98, 0x3000
	s_addc_u32 s99, s99, 0
	global_load_dword v178, v27, s[98:99] nt
	s_add_u32 s98, s98, 0x3000
	s_addc_u32 s99, s99, 0
	global_load_dword v179, v27, s[98:99] nt
	s_add_u32 s98, s98, 0x3000
	s_addc_u32 s99, s99, 0
	global_load_dword v180, v27, s[98:99] nt
	s_add_u32 s98, s98, 0x3000
	s_addc_u32 s99, s99, 0
	global_load_dword v181, v27, s[98:99] nt
	s_add_u32 s98, s98, 0x3000
	s_addc_u32 s99, s99, 0
	global_load_dword v182, v27, s[98:99] nt
	s_add_u32 s98, s98, 0x3000
	s_addc_u32 s99, s99, 0
	global_load_dword v183, v27, s[98:99] nt
	s_add_u32 s98, s98, 0x3000
	s_addc_u32 s99, s99, 0
	global_load_dword v184, v27, s[98:99] nt
	s_add_u32 s98, s98, 0x3000
	s_addc_u32 s99, s99, 0
	global_load_dword v185, v27, s[98:99] nt
	s_add_u32 s98, s98, 0x3000
	s_addc_u32 s99, s99, 0
	global_load_dword v186, v27, s[98:99] nt
	s_add_u32 s98, s98, 0x3000
	s_addc_u32 s99, s99, 0
	global_load_dword v187, v27, s[98:99] nt
	s_add_u32 s98, s98, 0x3000
	s_addc_u32 s99, s99, 0
	global_load_dword v188, v27, s[98:99] nt
	s_add_u32 s98, s98, 0x3000
	s_addc_u32 s99, s99, 0
	global_load_dword v189, v27, s[98:99] nt
	s_add_u32 s98, s98, 0x3000
	s_addc_u32 s99, s99, 0
	global_load_dword v190, v27, s[98:99] nt
	s_add_u32 s98, s98, 0x3000
	s_addc_u32 s99, s99, 0
	global_load_dword v191, v27, s[98:99] nt
	s_add_u32 s98, s98, 0x3000
	s_addc_u32 s99, s99, 0
	global_load_dword v192, v27, s[98:99] nt
	s_add_u32 s98, s98, 0x3000
	s_addc_u32 s99, s99, 0
	global_load_dword v193, v27, s[98:99] nt
	s_add_u32 s98, s98, 0x3000
	s_addc_u32 s99, s99, 0
	global_load_dword v194, v27, s[98:99] nt
	s_add_u32 s98, s98, 0x3000
	s_addc_u32 s99, s99, 0
	global_load_dword v195, v27, s[98:99] nt
	s_waitcnt vmcnt(63)
	v_mul_f32_e32 v28, 0xbfb8aa3b, v0
	v_mul_f32_e32 v29, 0xbfb8aa3b, v23
	v_mul_f32_e32 v30, 0xbfb8aa3b, v24
	v_mul_f32_e32 v31, 0xbfb8aa3b, v25
	v_mul_f32_e32 v32, 0xbfb8aa3b, v26
	v_exp_f32_e32 v28, v28
	v_exp_f32_e32 v29, v29
	v_exp_f32_e32 v30, v30
	v_exp_f32_e32 v31, v31
	v_exp_f32_e32 v32, v32
	v_add_f32_e32 v28, 1.0, v28
	v_add_f32_e32 v29, 1.0, v29
	v_add_f32_e32 v30, 1.0, v30
	v_add_f32_e32 v31, 1.0, v31
	v_add_f32_e32 v32, 1.0, v32
	v_rcp_f32_e32 v28, v28
	v_rcp_f32_e32 v29, v29
	v_rcp_f32_e32 v30, v30
	v_rcp_f32_e32 v31, v31
	v_rcp_f32_e32 v32, v32
	v_mul_f32_e32 v0, v0, v28
	v_mul_f32_e32 v23, v23, v29
	v_mul_f32_e32 v24, v24, v30
	v_mul_f32_e32 v25, v25, v31
	v_mul_f32_e32 v26, v26, v32
	v_mov_b32_e32 v10, 0
	v_mov_b32_e32 v11, 0
	v_mov_b32_e32 v8, 0
	v_mov_b32_e32 v9, 0
	v_mov_b32_e32 v22, 0
	v_readlane_b32 s12, v0, 0
	v_readlane_b32 s13, v23, 0
	v_readlane_b32 s14, v24, 0
	v_readlane_b32 s15, v25, 0
	v_readlane_b32 s16, v26, 0
	s_waitcnt vmcnt(63)
	v_pk_fma_f32 v[10:11], v[132:133], s[12:13], v[10:11] op_sel_hi:[0,1,1]
	v_pk_fma_f32 v[8:9], v[132:133], s[14:15], v[8:9] op_sel_hi:[0,1,1]
	v_fmac_f32_e32 v22, s16, v132
	v_readlane_b32 s12, v0, 1
	v_readlane_b32 s13, v23, 1
	v_readlane_b32 s14, v24, 1
	v_readlane_b32 s15, v25, 1
	v_readlane_b32 s16, v26, 1
	s_waitcnt vmcnt(62)
	v_pk_fma_f32 v[10:11], v[132:133], s[12:13], v[10:11] op_sel:[1,0,0] op_sel_hi:[1,1,1]
	v_pk_fma_f32 v[8:9], v[132:133], s[14:15], v[8:9] op_sel:[1,0,0] op_sel_hi:[1,1,1]
	v_fmac_f32_e32 v22, s16, v133
	v_readlane_b32 s12, v0, 2
	v_readlane_b32 s13, v23, 2
	v_readlane_b32 s14, v24, 2
	v_readlane_b32 s15, v25, 2
	v_readlane_b32 s16, v26, 2
	s_waitcnt vmcnt(61)
	v_pk_fma_f32 v[10:11], v[134:135], s[12:13], v[10:11] op_sel_hi:[0,1,1]
	v_pk_fma_f32 v[8:9], v[134:135], s[14:15], v[8:9] op_sel_hi:[0,1,1]
	v_fmac_f32_e32 v22, s16, v134
	v_readlane_b32 s12, v0, 3
	v_readlane_b32 s13, v23, 3
	v_readlane_b32 s14, v24, 3
	v_readlane_b32 s15, v25, 3
	v_readlane_b32 s16, v26, 3
	s_waitcnt vmcnt(60)
	v_pk_fma_f32 v[10:11], v[134:135], s[12:13], v[10:11] op_sel:[1,0,0] op_sel_hi:[1,1,1]
	v_pk_fma_f32 v[8:9], v[134:135], s[14:15], v[8:9] op_sel:[1,0,0] op_sel_hi:[1,1,1]
	v_fmac_f32_e32 v22, s16, v135
	v_readlane_b32 s12, v0, 4
	v_readlane_b32 s13, v23, 4
	v_readlane_b32 s14, v24, 4
	v_readlane_b32 s15, v25, 4
	v_readlane_b32 s16, v26, 4
	s_waitcnt vmcnt(59)
	v_pk_fma_f32 v[10:11], v[136:137], s[12:13], v[10:11] op_sel_hi:[0,1,1]
	v_pk_fma_f32 v[8:9], v[136:137], s[14:15], v[8:9] op_sel_hi:[0,1,1]
	v_fmac_f32_e32 v22, s16, v136
	v_readlane_b32 s12, v0, 5
	v_readlane_b32 s13, v23, 5
	v_readlane_b32 s14, v24, 5
	v_readlane_b32 s15, v25, 5
	v_readlane_b32 s16, v26, 5
	s_waitcnt vmcnt(58)
	v_pk_fma_f32 v[10:11], v[136:137], s[12:13], v[10:11] op_sel:[1,0,0] op_sel_hi:[1,1,1]
	v_pk_fma_f32 v[8:9], v[136:137], s[14:15], v[8:9] op_sel:[1,0,0] op_sel_hi:[1,1,1]
	v_fmac_f32_e32 v22, s16, v137
	v_readlane_b32 s12, v0, 6
	v_readlane_b32 s13, v23, 6
	v_readlane_b32 s14, v24, 6
	v_readlane_b32 s15, v25, 6
	v_readlane_b32 s16, v26, 6
	s_waitcnt vmcnt(57)
	v_pk_fma_f32 v[10:11], v[138:139], s[12:13], v[10:11] op_sel_hi:[0,1,1]
	v_pk_fma_f32 v[8:9], v[138:139], s[14:15], v[8:9] op_sel_hi:[0,1,1]
	v_fmac_f32_e32 v22, s16, v138
	v_readlane_b32 s12, v0, 7
	v_readlane_b32 s13, v23, 7
	v_readlane_b32 s14, v24, 7
	v_readlane_b32 s15, v25, 7
	v_readlane_b32 s16, v26, 7
	s_waitcnt vmcnt(56)
	v_pk_fma_f32 v[10:11], v[138:139], s[12:13], v[10:11] op_sel:[1,0,0] op_sel_hi:[1,1,1]
	v_pk_fma_f32 v[8:9], v[138:139], s[14:15], v[8:9] op_sel:[1,0,0] op_sel_hi:[1,1,1]
	v_fmac_f32_e32 v22, s16, v139
	v_readlane_b32 s12, v0, 8
	v_readlane_b32 s13, v23, 8
	v_readlane_b32 s14, v24, 8
	v_readlane_b32 s15, v25, 8
	v_readlane_b32 s16, v26, 8
	s_waitcnt vmcnt(55)
	v_pk_fma_f32 v[10:11], v[140:141], s[12:13], v[10:11] op_sel_hi:[0,1,1]
	v_pk_fma_f32 v[8:9], v[140:141], s[14:15], v[8:9] op_sel_hi:[0,1,1]
	v_fmac_f32_e32 v22, s16, v140
	v_readlane_b32 s12, v0, 9
	v_readlane_b32 s13, v23, 9
	v_readlane_b32 s14, v24, 9
	v_readlane_b32 s15, v25, 9
	v_readlane_b32 s16, v26, 9
	s_waitcnt vmcnt(54)
	v_pk_fma_f32 v[10:11], v[140:141], s[12:13], v[10:11] op_sel:[1,0,0] op_sel_hi:[1,1,1]
	v_pk_fma_f32 v[8:9], v[140:141], s[14:15], v[8:9] op_sel:[1,0,0] op_sel_hi:[1,1,1]
	v_fmac_f32_e32 v22, s16, v141
	v_readlane_b32 s12, v0, 10
	v_readlane_b32 s13, v23, 10
	v_readlane_b32 s14, v24, 10
	v_readlane_b32 s15, v25, 10
	v_readlane_b32 s16, v26, 10
	s_waitcnt vmcnt(53)
	v_pk_fma_f32 v[10:11], v[142:143], s[12:13], v[10:11] op_sel_hi:[0,1,1]
	v_pk_fma_f32 v[8:9], v[142:143], s[14:15], v[8:9] op_sel_hi:[0,1,1]
	v_fmac_f32_e32 v22, s16, v142
	v_readlane_b32 s12, v0, 11
	v_readlane_b32 s13, v23, 11
	v_readlane_b32 s14, v24, 11
	v_readlane_b32 s15, v25, 11
	v_readlane_b32 s16, v26, 11
	s_waitcnt vmcnt(52)
	v_pk_fma_f32 v[10:11], v[142:143], s[12:13], v[10:11] op_sel:[1,0,0] op_sel_hi:[1,1,1]
	v_pk_fma_f32 v[8:9], v[142:143], s[14:15], v[8:9] op_sel:[1,0,0] op_sel_hi:[1,1,1]
	v_fmac_f32_e32 v22, s16, v143
	v_readlane_b32 s12, v0, 12
	v_readlane_b32 s13, v23, 12
	v_readlane_b32 s14, v24, 12
	v_readlane_b32 s15, v25, 12
	v_readlane_b32 s16, v26, 12
	s_waitcnt vmcnt(51)
	v_pk_fma_f32 v[10:11], v[144:145], s[12:13], v[10:11] op_sel_hi:[0,1,1]
	v_pk_fma_f32 v[8:9], v[144:145], s[14:15], v[8:9] op_sel_hi:[0,1,1]
	v_fmac_f32_e32 v22, s16, v144
	v_readlane_b32 s12, v0, 13
	v_readlane_b32 s13, v23, 13
	v_readlane_b32 s14, v24, 13
	v_readlane_b32 s15, v25, 13
	v_readlane_b32 s16, v26, 13
	s_waitcnt vmcnt(50)
	v_pk_fma_f32 v[10:11], v[144:145], s[12:13], v[10:11] op_sel:[1,0,0] op_sel_hi:[1,1,1]
	v_pk_fma_f32 v[8:9], v[144:145], s[14:15], v[8:9] op_sel:[1,0,0] op_sel_hi:[1,1,1]
	v_fmac_f32_e32 v22, s16, v145
	v_readlane_b32 s12, v0, 14
	v_readlane_b32 s13, v23, 14
	v_readlane_b32 s14, v24, 14
	v_readlane_b32 s15, v25, 14
	v_readlane_b32 s16, v26, 14
	s_waitcnt vmcnt(49)
	v_pk_fma_f32 v[10:11], v[146:147], s[12:13], v[10:11] op_sel_hi:[0,1,1]
	v_pk_fma_f32 v[8:9], v[146:147], s[14:15], v[8:9] op_sel_hi:[0,1,1]
	v_fmac_f32_e32 v22, s16, v146
	v_readlane_b32 s12, v0, 15
	v_readlane_b32 s13, v23, 15
	v_readlane_b32 s14, v24, 15
	v_readlane_b32 s15, v25, 15
	v_readlane_b32 s16, v26, 15
	s_waitcnt vmcnt(48)
	v_pk_fma_f32 v[10:11], v[146:147], s[12:13], v[10:11] op_sel:[1,0,0] op_sel_hi:[1,1,1]
	v_pk_fma_f32 v[8:9], v[146:147], s[14:15], v[8:9] op_sel:[1,0,0] op_sel_hi:[1,1,1]
	v_fmac_f32_e32 v22, s16, v147
	v_readlane_b32 s12, v0, 16
	v_readlane_b32 s13, v23, 16
	v_readlane_b32 s14, v24, 16
	v_readlane_b32 s15, v25, 16
	v_readlane_b32 s16, v26, 16
	s_waitcnt vmcnt(47)
	v_pk_fma_f32 v[10:11], v[148:149], s[12:13], v[10:11] op_sel_hi:[0,1,1]
	v_pk_fma_f32 v[8:9], v[148:149], s[14:15], v[8:9] op_sel_hi:[0,1,1]
	v_fmac_f32_e32 v22, s16, v148
	v_readlane_b32 s12, v0, 17
	v_readlane_b32 s13, v23, 17
	v_readlane_b32 s14, v24, 17
	v_readlane_b32 s15, v25, 17
	v_readlane_b32 s16, v26, 17
	s_waitcnt vmcnt(46)
	v_pk_fma_f32 v[10:11], v[148:149], s[12:13], v[10:11] op_sel:[1,0,0] op_sel_hi:[1,1,1]
	v_pk_fma_f32 v[8:9], v[148:149], s[14:15], v[8:9] op_sel:[1,0,0] op_sel_hi:[1,1,1]
	v_fmac_f32_e32 v22, s16, v149
	v_readlane_b32 s12, v0, 18
	v_readlane_b32 s13, v23, 18
	v_readlane_b32 s14, v24, 18
	v_readlane_b32 s15, v25, 18
	v_readlane_b32 s16, v26, 18
	s_waitcnt vmcnt(45)
	v_pk_fma_f32 v[10:11], v[150:151], s[12:13], v[10:11] op_sel_hi:[0,1,1]
	v_pk_fma_f32 v[8:9], v[150:151], s[14:15], v[8:9] op_sel_hi:[0,1,1]
	v_fmac_f32_e32 v22, s16, v150
	v_readlane_b32 s12, v0, 19
	v_readlane_b32 s13, v23, 19
	v_readlane_b32 s14, v24, 19
	v_readlane_b32 s15, v25, 19
	v_readlane_b32 s16, v26, 19
	s_waitcnt vmcnt(44)
	v_pk_fma_f32 v[10:11], v[150:151], s[12:13], v[10:11] op_sel:[1,0,0] op_sel_hi:[1,1,1]
	v_pk_fma_f32 v[8:9], v[150:151], s[14:15], v[8:9] op_sel:[1,0,0] op_sel_hi:[1,1,1]
	v_fmac_f32_e32 v22, s16, v151
	v_readlane_b32 s12, v0, 20
	v_readlane_b32 s13, v23, 20
	v_readlane_b32 s14, v24, 20
	v_readlane_b32 s15, v25, 20
	v_readlane_b32 s16, v26, 20
	s_waitcnt vmcnt(43)
	v_pk_fma_f32 v[10:11], v[152:153], s[12:13], v[10:11] op_sel_hi:[0,1,1]
	v_pk_fma_f32 v[8:9], v[152:153], s[14:15], v[8:9] op_sel_hi:[0,1,1]
	v_fmac_f32_e32 v22, s16, v152
	v_readlane_b32 s12, v0, 21
	v_readlane_b32 s13, v23, 21
	v_readlane_b32 s14, v24, 21
	v_readlane_b32 s15, v25, 21
	v_readlane_b32 s16, v26, 21
	s_waitcnt vmcnt(42)
	v_pk_fma_f32 v[10:11], v[152:153], s[12:13], v[10:11] op_sel:[1,0,0] op_sel_hi:[1,1,1]
	v_pk_fma_f32 v[8:9], v[152:153], s[14:15], v[8:9] op_sel:[1,0,0] op_sel_hi:[1,1,1]
	v_fmac_f32_e32 v22, s16, v153
	v_readlane_b32 s12, v0, 22
	v_readlane_b32 s13, v23, 22
	v_readlane_b32 s14, v24, 22
	v_readlane_b32 s15, v25, 22
	v_readlane_b32 s16, v26, 22
	s_waitcnt vmcnt(41)
	v_pk_fma_f32 v[10:11], v[154:155], s[12:13], v[10:11] op_sel_hi:[0,1,1]
	v_pk_fma_f32 v[8:9], v[154:155], s[14:15], v[8:9] op_sel_hi:[0,1,1]
	v_fmac_f32_e32 v22, s16, v154
	v_readlane_b32 s12, v0, 23
	v_readlane_b32 s13, v23, 23
	v_readlane_b32 s14, v24, 23
	v_readlane_b32 s15, v25, 23
	v_readlane_b32 s16, v26, 23
	s_waitcnt vmcnt(40)
	v_pk_fma_f32 v[10:11], v[154:155], s[12:13], v[10:11] op_sel:[1,0,0] op_sel_hi:[1,1,1]
	v_pk_fma_f32 v[8:9], v[154:155], s[14:15], v[8:9] op_sel:[1,0,0] op_sel_hi:[1,1,1]
	v_fmac_f32_e32 v22, s16, v155
	v_readlane_b32 s12, v0, 24
	v_readlane_b32 s13, v23, 24
	v_readlane_b32 s14, v24, 24
	v_readlane_b32 s15, v25, 24
	v_readlane_b32 s16, v26, 24
	s_waitcnt vmcnt(39)
	v_pk_fma_f32 v[10:11], v[156:157], s[12:13], v[10:11] op_sel_hi:[0,1,1]
	v_pk_fma_f32 v[8:9], v[156:157], s[14:15], v[8:9] op_sel_hi:[0,1,1]
	v_fmac_f32_e32 v22, s16, v156
	v_readlane_b32 s12, v0, 25
	v_readlane_b32 s13, v23, 25
	v_readlane_b32 s14, v24, 25
	v_readlane_b32 s15, v25, 25
	v_readlane_b32 s16, v26, 25
	s_waitcnt vmcnt(38)
	v_pk_fma_f32 v[10:11], v[156:157], s[12:13], v[10:11] op_sel:[1,0,0] op_sel_hi:[1,1,1]
	v_pk_fma_f32 v[8:9], v[156:157], s[14:15], v[8:9] op_sel:[1,0,0] op_sel_hi:[1,1,1]
	v_fmac_f32_e32 v22, s16, v157
	v_readlane_b32 s12, v0, 26
	v_readlane_b32 s13, v23, 26
	v_readlane_b32 s14, v24, 26
	v_readlane_b32 s15, v25, 26
	v_readlane_b32 s16, v26, 26
	s_waitcnt vmcnt(37)
	v_pk_fma_f32 v[10:11], v[158:159], s[12:13], v[10:11] op_sel_hi:[0,1,1]
	v_pk_fma_f32 v[8:9], v[158:159], s[14:15], v[8:9] op_sel_hi:[0,1,1]
	v_fmac_f32_e32 v22, s16, v158
	v_readlane_b32 s12, v0, 27
	v_readlane_b32 s13, v23, 27
	v_readlane_b32 s14, v24, 27
	v_readlane_b32 s15, v25, 27
	v_readlane_b32 s16, v26, 27
	s_waitcnt vmcnt(36)
	v_pk_fma_f32 v[10:11], v[158:159], s[12:13], v[10:11] op_sel:[1,0,0] op_sel_hi:[1,1,1]
	v_pk_fma_f32 v[8:9], v[158:159], s[14:15], v[8:9] op_sel:[1,0,0] op_sel_hi:[1,1,1]
	v_fmac_f32_e32 v22, s16, v159
	v_readlane_b32 s12, v0, 28
	v_readlane_b32 s13, v23, 28
	v_readlane_b32 s14, v24, 28
	v_readlane_b32 s15, v25, 28
	v_readlane_b32 s16, v26, 28
	s_waitcnt vmcnt(35)
	v_pk_fma_f32 v[10:11], v[160:161], s[12:13], v[10:11] op_sel_hi:[0,1,1]
	v_pk_fma_f32 v[8:9], v[160:161], s[14:15], v[8:9] op_sel_hi:[0,1,1]
	v_fmac_f32_e32 v22, s16, v160
	v_readlane_b32 s12, v0, 29
	v_readlane_b32 s13, v23, 29
	v_readlane_b32 s14, v24, 29
	v_readlane_b32 s15, v25, 29
	v_readlane_b32 s16, v26, 29
	s_waitcnt vmcnt(34)
	v_pk_fma_f32 v[10:11], v[160:161], s[12:13], v[10:11] op_sel:[1,0,0] op_sel_hi:[1,1,1]
	v_pk_fma_f32 v[8:9], v[160:161], s[14:15], v[8:9] op_sel:[1,0,0] op_sel_hi:[1,1,1]
	v_fmac_f32_e32 v22, s16, v161
	v_readlane_b32 s12, v0, 30
	v_readlane_b32 s13, v23, 30
	v_readlane_b32 s14, v24, 30
	v_readlane_b32 s15, v25, 30
	v_readlane_b32 s16, v26, 30
	s_waitcnt vmcnt(33)
	v_pk_fma_f32 v[10:11], v[162:163], s[12:13], v[10:11] op_sel_hi:[0,1,1]
	v_pk_fma_f32 v[8:9], v[162:163], s[14:15], v[8:9] op_sel_hi:[0,1,1]
	v_fmac_f32_e32 v22, s16, v162
	v_readlane_b32 s12, v0, 31
	v_readlane_b32 s13, v23, 31
	v_readlane_b32 s14, v24, 31
	v_readlane_b32 s15, v25, 31
	v_readlane_b32 s16, v26, 31
	s_waitcnt vmcnt(32)
	v_pk_fma_f32 v[10:11], v[162:163], s[12:13], v[10:11] op_sel:[1,0,0] op_sel_hi:[1,1,1]
	v_pk_fma_f32 v[8:9], v[162:163], s[14:15], v[8:9] op_sel:[1,0,0] op_sel_hi:[1,1,1]
	v_fmac_f32_e32 v22, s16, v163
	v_readlane_b32 s12, v0, 32
	v_readlane_b32 s13, v23, 32
	v_readlane_b32 s14, v24, 32
	v_readlane_b32 s15, v25, 32
	v_readlane_b32 s16, v26, 32
	s_waitcnt vmcnt(31)
	v_pk_fma_f32 v[10:11], v[164:165], s[12:13], v[10:11] op_sel_hi:[0,1,1]
	v_pk_fma_f32 v[8:9], v[164:165], s[14:15], v[8:9] op_sel_hi:[0,1,1]
	v_fmac_f32_e32 v22, s16, v164
	v_readlane_b32 s12, v0, 33
	v_readlane_b32 s13, v23, 33
	v_readlane_b32 s14, v24, 33
	v_readlane_b32 s15, v25, 33
	v_readlane_b32 s16, v26, 33
	s_waitcnt vmcnt(30)
	v_pk_fma_f32 v[10:11], v[164:165], s[12:13], v[10:11] op_sel:[1,0,0] op_sel_hi:[1,1,1]
	v_pk_fma_f32 v[8:9], v[164:165], s[14:15], v[8:9] op_sel:[1,0,0] op_sel_hi:[1,1,1]
	v_fmac_f32_e32 v22, s16, v165
	v_readlane_b32 s12, v0, 34
	v_readlane_b32 s13, v23, 34
	v_readlane_b32 s14, v24, 34
	v_readlane_b32 s15, v25, 34
	v_readlane_b32 s16, v26, 34
	s_waitcnt vmcnt(29)
	v_pk_fma_f32 v[10:11], v[166:167], s[12:13], v[10:11] op_sel_hi:[0,1,1]
	v_pk_fma_f32 v[8:9], v[166:167], s[14:15], v[8:9] op_sel_hi:[0,1,1]
	v_fmac_f32_e32 v22, s16, v166
	v_readlane_b32 s12, v0, 35
	v_readlane_b32 s13, v23, 35
	v_readlane_b32 s14, v24, 35
	v_readlane_b32 s15, v25, 35
	v_readlane_b32 s16, v26, 35
	s_waitcnt vmcnt(28)
	v_pk_fma_f32 v[10:11], v[166:167], s[12:13], v[10:11] op_sel:[1,0,0] op_sel_hi:[1,1,1]
	v_pk_fma_f32 v[8:9], v[166:167], s[14:15], v[8:9] op_sel:[1,0,0] op_sel_hi:[1,1,1]
	v_fmac_f32_e32 v22, s16, v167
	v_readlane_b32 s12, v0, 36
	v_readlane_b32 s13, v23, 36
	v_readlane_b32 s14, v24, 36
	v_readlane_b32 s15, v25, 36
	v_readlane_b32 s16, v26, 36
	s_waitcnt vmcnt(27)
	v_pk_fma_f32 v[10:11], v[168:169], s[12:13], v[10:11] op_sel_hi:[0,1,1]
	v_pk_fma_f32 v[8:9], v[168:169], s[14:15], v[8:9] op_sel_hi:[0,1,1]
	v_fmac_f32_e32 v22, s16, v168
	v_readlane_b32 s12, v0, 37
	v_readlane_b32 s13, v23, 37
	v_readlane_b32 s14, v24, 37
	v_readlane_b32 s15, v25, 37
	v_readlane_b32 s16, v26, 37
	s_waitcnt vmcnt(26)
	v_pk_fma_f32 v[10:11], v[168:169], s[12:13], v[10:11] op_sel:[1,0,0] op_sel_hi:[1,1,1]
	v_pk_fma_f32 v[8:9], v[168:169], s[14:15], v[8:9] op_sel:[1,0,0] op_sel_hi:[1,1,1]
	v_fmac_f32_e32 v22, s16, v169
	v_readlane_b32 s12, v0, 38
	v_readlane_b32 s13, v23, 38
	v_readlane_b32 s14, v24, 38
	v_readlane_b32 s15, v25, 38
	v_readlane_b32 s16, v26, 38
	s_waitcnt vmcnt(25)
	v_pk_fma_f32 v[10:11], v[170:171], s[12:13], v[10:11] op_sel_hi:[0,1,1]
	v_pk_fma_f32 v[8:9], v[170:171], s[14:15], v[8:9] op_sel_hi:[0,1,1]
	v_fmac_f32_e32 v22, s16, v170
	v_readlane_b32 s12, v0, 39
	v_readlane_b32 s13, v23, 39
	v_readlane_b32 s14, v24, 39
	v_readlane_b32 s15, v25, 39
	v_readlane_b32 s16, v26, 39
	s_waitcnt vmcnt(24)
	v_pk_fma_f32 v[10:11], v[170:171], s[12:13], v[10:11] op_sel:[1,0,0] op_sel_hi:[1,1,1]
	v_pk_fma_f32 v[8:9], v[170:171], s[14:15], v[8:9] op_sel:[1,0,0] op_sel_hi:[1,1,1]
	v_fmac_f32_e32 v22, s16, v171
	v_readlane_b32 s12, v0, 40
	v_readlane_b32 s13, v23, 40
	v_readlane_b32 s14, v24, 40
	v_readlane_b32 s15, v25, 40
	v_readlane_b32 s16, v26, 40
	s_waitcnt vmcnt(23)
	v_pk_fma_f32 v[10:11], v[172:173], s[12:13], v[10:11] op_sel_hi:[0,1,1]
	v_pk_fma_f32 v[8:9], v[172:173], s[14:15], v[8:9] op_sel_hi:[0,1,1]
	v_fmac_f32_e32 v22, s16, v172
	v_readlane_b32 s12, v0, 41
	v_readlane_b32 s13, v23, 41
	v_readlane_b32 s14, v24, 41
	v_readlane_b32 s15, v25, 41
	v_readlane_b32 s16, v26, 41
	s_waitcnt vmcnt(22)
	v_pk_fma_f32 v[10:11], v[172:173], s[12:13], v[10:11] op_sel:[1,0,0] op_sel_hi:[1,1,1]
	v_pk_fma_f32 v[8:9], v[172:173], s[14:15], v[8:9] op_sel:[1,0,0] op_sel_hi:[1,1,1]
	v_fmac_f32_e32 v22, s16, v173
	v_readlane_b32 s12, v0, 42
	v_readlane_b32 s13, v23, 42
	v_readlane_b32 s14, v24, 42
	v_readlane_b32 s15, v25, 42
	v_readlane_b32 s16, v26, 42
	s_waitcnt vmcnt(21)
	v_pk_fma_f32 v[10:11], v[174:175], s[12:13], v[10:11] op_sel_hi:[0,1,1]
	v_pk_fma_f32 v[8:9], v[174:175], s[14:15], v[8:9] op_sel_hi:[0,1,1]
	v_fmac_f32_e32 v22, s16, v174
	v_readlane_b32 s12, v0, 43
	v_readlane_b32 s13, v23, 43
	v_readlane_b32 s14, v24, 43
	v_readlane_b32 s15, v25, 43
	v_readlane_b32 s16, v26, 43
	s_waitcnt vmcnt(20)
	v_pk_fma_f32 v[10:11], v[174:175], s[12:13], v[10:11] op_sel:[1,0,0] op_sel_hi:[1,1,1]
	v_pk_fma_f32 v[8:9], v[174:175], s[14:15], v[8:9] op_sel:[1,0,0] op_sel_hi:[1,1,1]
	v_fmac_f32_e32 v22, s16, v175
	v_readlane_b32 s12, v0, 44
	v_readlane_b32 s13, v23, 44
	v_readlane_b32 s14, v24, 44
	v_readlane_b32 s15, v25, 44
	v_readlane_b32 s16, v26, 44
	s_waitcnt vmcnt(19)
	v_pk_fma_f32 v[10:11], v[176:177], s[12:13], v[10:11] op_sel_hi:[0,1,1]
	v_pk_fma_f32 v[8:9], v[176:177], s[14:15], v[8:9] op_sel_hi:[0,1,1]
	v_fmac_f32_e32 v22, s16, v176
	v_readlane_b32 s12, v0, 45
	v_readlane_b32 s13, v23, 45
	v_readlane_b32 s14, v24, 45
	v_readlane_b32 s15, v25, 45
	v_readlane_b32 s16, v26, 45
	s_waitcnt vmcnt(18)
	v_pk_fma_f32 v[10:11], v[176:177], s[12:13], v[10:11] op_sel:[1,0,0] op_sel_hi:[1,1,1]
	v_pk_fma_f32 v[8:9], v[176:177], s[14:15], v[8:9] op_sel:[1,0,0] op_sel_hi:[1,1,1]
	v_fmac_f32_e32 v22, s16, v177
	v_readlane_b32 s12, v0, 46
	v_readlane_b32 s13, v23, 46
	v_readlane_b32 s14, v24, 46
	v_readlane_b32 s15, v25, 46
	v_readlane_b32 s16, v26, 46
	s_waitcnt vmcnt(17)
	v_pk_fma_f32 v[10:11], v[178:179], s[12:13], v[10:11] op_sel_hi:[0,1,1]
	v_pk_fma_f32 v[8:9], v[178:179], s[14:15], v[8:9] op_sel_hi:[0,1,1]
	v_fmac_f32_e32 v22, s16, v178
	v_readlane_b32 s12, v0, 47
	v_readlane_b32 s13, v23, 47
	v_readlane_b32 s14, v24, 47
	v_readlane_b32 s15, v25, 47
	v_readlane_b32 s16, v26, 47
	s_waitcnt vmcnt(16)
	v_pk_fma_f32 v[10:11], v[178:179], s[12:13], v[10:11] op_sel:[1,0,0] op_sel_hi:[1,1,1]
	v_pk_fma_f32 v[8:9], v[178:179], s[14:15], v[8:9] op_sel:[1,0,0] op_sel_hi:[1,1,1]
	v_fmac_f32_e32 v22, s16, v179
	v_readlane_b32 s12, v0, 48
	v_readlane_b32 s13, v23, 48
	v_readlane_b32 s14, v24, 48
	v_readlane_b32 s15, v25, 48
	v_readlane_b32 s16, v26, 48
	s_waitcnt vmcnt(15)
	v_pk_fma_f32 v[10:11], v[180:181], s[12:13], v[10:11] op_sel_hi:[0,1,1]
	v_pk_fma_f32 v[8:9], v[180:181], s[14:15], v[8:9] op_sel_hi:[0,1,1]
	v_fmac_f32_e32 v22, s16, v180
	v_readlane_b32 s12, v0, 49
	v_readlane_b32 s13, v23, 49
	v_readlane_b32 s14, v24, 49
	v_readlane_b32 s15, v25, 49
	v_readlane_b32 s16, v26, 49
	s_waitcnt vmcnt(14)
	v_pk_fma_f32 v[10:11], v[180:181], s[12:13], v[10:11] op_sel:[1,0,0] op_sel_hi:[1,1,1]
	v_pk_fma_f32 v[8:9], v[180:181], s[14:15], v[8:9] op_sel:[1,0,0] op_sel_hi:[1,1,1]
	v_fmac_f32_e32 v22, s16, v181
	v_readlane_b32 s12, v0, 50
	v_readlane_b32 s13, v23, 50
	v_readlane_b32 s14, v24, 50
	v_readlane_b32 s15, v25, 50
	v_readlane_b32 s16, v26, 50
	s_waitcnt vmcnt(13)
	v_pk_fma_f32 v[10:11], v[182:183], s[12:13], v[10:11] op_sel_hi:[0,1,1]
	v_pk_fma_f32 v[8:9], v[182:183], s[14:15], v[8:9] op_sel_hi:[0,1,1]
	v_fmac_f32_e32 v22, s16, v182
	v_readlane_b32 s12, v0, 51
	v_readlane_b32 s13, v23, 51
	v_readlane_b32 s14, v24, 51
	v_readlane_b32 s15, v25, 51
	v_readlane_b32 s16, v26, 51
	s_waitcnt vmcnt(12)
	v_pk_fma_f32 v[10:11], v[182:183], s[12:13], v[10:11] op_sel:[1,0,0] op_sel_hi:[1,1,1]
	v_pk_fma_f32 v[8:9], v[182:183], s[14:15], v[8:9] op_sel:[1,0,0] op_sel_hi:[1,1,1]
	v_fmac_f32_e32 v22, s16, v183
	v_readlane_b32 s12, v0, 52
	v_readlane_b32 s13, v23, 52
	v_readlane_b32 s14, v24, 52
	v_readlane_b32 s15, v25, 52
	v_readlane_b32 s16, v26, 52
	s_waitcnt vmcnt(11)
	v_pk_fma_f32 v[10:11], v[184:185], s[12:13], v[10:11] op_sel_hi:[0,1,1]
	v_pk_fma_f32 v[8:9], v[184:185], s[14:15], v[8:9] op_sel_hi:[0,1,1]
	v_fmac_f32_e32 v22, s16, v184
	v_readlane_b32 s12, v0, 53
	v_readlane_b32 s13, v23, 53
	v_readlane_b32 s14, v24, 53
	v_readlane_b32 s15, v25, 53
	v_readlane_b32 s16, v26, 53
	s_waitcnt vmcnt(10)
	v_pk_fma_f32 v[10:11], v[184:185], s[12:13], v[10:11] op_sel:[1,0,0] op_sel_hi:[1,1,1]
	v_pk_fma_f32 v[8:9], v[184:185], s[14:15], v[8:9] op_sel:[1,0,0] op_sel_hi:[1,1,1]
	v_fmac_f32_e32 v22, s16, v185
	v_readlane_b32 s12, v0, 54
	v_readlane_b32 s13, v23, 54
	v_readlane_b32 s14, v24, 54
	v_readlane_b32 s15, v25, 54
	v_readlane_b32 s16, v26, 54
	s_waitcnt vmcnt(9)
	v_pk_fma_f32 v[10:11], v[186:187], s[12:13], v[10:11] op_sel_hi:[0,1,1]
	v_pk_fma_f32 v[8:9], v[186:187], s[14:15], v[8:9] op_sel_hi:[0,1,1]
	v_fmac_f32_e32 v22, s16, v186
	v_readlane_b32 s12, v0, 55
	v_readlane_b32 s13, v23, 55
	v_readlane_b32 s14, v24, 55
	v_readlane_b32 s15, v25, 55
	v_readlane_b32 s16, v26, 55
	s_waitcnt vmcnt(8)
	v_pk_fma_f32 v[10:11], v[186:187], s[12:13], v[10:11] op_sel:[1,0,0] op_sel_hi:[1,1,1]
	v_pk_fma_f32 v[8:9], v[186:187], s[14:15], v[8:9] op_sel:[1,0,0] op_sel_hi:[1,1,1]
	v_fmac_f32_e32 v22, s16, v187
	v_readlane_b32 s12, v0, 56
	v_readlane_b32 s13, v23, 56
	v_readlane_b32 s14, v24, 56
	v_readlane_b32 s15, v25, 56
	v_readlane_b32 s16, v26, 56
	s_waitcnt vmcnt(7)
	v_pk_fma_f32 v[10:11], v[188:189], s[12:13], v[10:11] op_sel_hi:[0,1,1]
	v_pk_fma_f32 v[8:9], v[188:189], s[14:15], v[8:9] op_sel_hi:[0,1,1]
	v_fmac_f32_e32 v22, s16, v188
	v_readlane_b32 s12, v0, 57
	v_readlane_b32 s13, v23, 57
	v_readlane_b32 s14, v24, 57
	v_readlane_b32 s15, v25, 57
	v_readlane_b32 s16, v26, 57
	s_waitcnt vmcnt(6)
	v_pk_fma_f32 v[10:11], v[188:189], s[12:13], v[10:11] op_sel:[1,0,0] op_sel_hi:[1,1,1]
	v_pk_fma_f32 v[8:9], v[188:189], s[14:15], v[8:9] op_sel:[1,0,0] op_sel_hi:[1,1,1]
	v_fmac_f32_e32 v22, s16, v189
	v_readlane_b32 s12, v0, 58
	v_readlane_b32 s13, v23, 58
	v_readlane_b32 s14, v24, 58
	v_readlane_b32 s15, v25, 58
	v_readlane_b32 s16, v26, 58
	s_waitcnt vmcnt(5)
	v_pk_fma_f32 v[10:11], v[190:191], s[12:13], v[10:11] op_sel_hi:[0,1,1]
	v_pk_fma_f32 v[8:9], v[190:191], s[14:15], v[8:9] op_sel_hi:[0,1,1]
	v_fmac_f32_e32 v22, s16, v190
	v_readlane_b32 s12, v0, 59
	v_readlane_b32 s13, v23, 59
	v_readlane_b32 s14, v24, 59
	v_readlane_b32 s15, v25, 59
	v_readlane_b32 s16, v26, 59
	s_waitcnt vmcnt(4)
	v_pk_fma_f32 v[10:11], v[190:191], s[12:13], v[10:11] op_sel:[1,0,0] op_sel_hi:[1,1,1]
	v_pk_fma_f32 v[8:9], v[190:191], s[14:15], v[8:9] op_sel:[1,0,0] op_sel_hi:[1,1,1]
	v_fmac_f32_e32 v22, s16, v191
	v_readlane_b32 s12, v0, 60
	v_readlane_b32 s13, v23, 60
	v_readlane_b32 s14, v24, 60
	v_readlane_b32 s15, v25, 60
	v_readlane_b32 s16, v26, 60
	s_waitcnt vmcnt(3)
	v_pk_fma_f32 v[10:11], v[192:193], s[12:13], v[10:11] op_sel_hi:[0,1,1]
	v_pk_fma_f32 v[8:9], v[192:193], s[14:15], v[8:9] op_sel_hi:[0,1,1]
	v_fmac_f32_e32 v22, s16, v192
	v_readlane_b32 s12, v0, 61
	v_readlane_b32 s13, v23, 61
	v_readlane_b32 s14, v24, 61
	v_readlane_b32 s15, v25, 61
	v_readlane_b32 s16, v26, 61
	s_waitcnt vmcnt(2)
	v_pk_fma_f32 v[10:11], v[192:193], s[12:13], v[10:11] op_sel:[1,0,0] op_sel_hi:[1,1,1]
	v_pk_fma_f32 v[8:9], v[192:193], s[14:15], v[8:9] op_sel:[1,0,0] op_sel_hi:[1,1,1]
	v_fmac_f32_e32 v22, s16, v193
	v_readlane_b32 s12, v0, 62
	v_readlane_b32 s13, v23, 62
	v_readlane_b32 s14, v24, 62
	v_readlane_b32 s15, v25, 62
	v_readlane_b32 s16, v26, 62
	s_waitcnt vmcnt(1)
	v_pk_fma_f32 v[10:11], v[194:195], s[12:13], v[10:11] op_sel_hi:[0,1,1]
	v_pk_fma_f32 v[8:9], v[194:195], s[14:15], v[8:9] op_sel_hi:[0,1,1]
	v_fmac_f32_e32 v22, s16, v194
	v_readlane_b32 s12, v0, 63
	v_readlane_b32 s13, v23, 63
	v_readlane_b32 s14, v24, 63
	v_readlane_b32 s15, v25, 63
	v_readlane_b32 s16, v26, 63
	s_waitcnt vmcnt(0)
	v_pk_fma_f32 v[10:11], v[194:195], s[12:13], v[10:11] op_sel:[1,0,0] op_sel_hi:[1,1,1]
	v_pk_fma_f32 v[8:9], v[194:195], s[14:15], v[8:9] op_sel:[1,0,0] op_sel_hi:[1,1,1]
	v_fmac_f32_e32 v22, s16, v195
	s_and_b32 s8, s3, 3
	s_lshl_b32 s8, s8, 8
	s_add_i32 s8, s8, 0x10000
	v_add_u32_e32 v33, s8, v27
	s_cmp_eq_u32 s5, 0
	s_cbranch_scc1 .Lmp_lo
	ds_write_b32 v33, v10
	ds_write_b32 v33, v11 offset:1024
	ds_write_b32 v33, v8 offset:2048
	ds_write_b32 v33, v9 offset:3072
	ds_write_b32 v33, v22 offset:4096
.Lmp_lo:
	s_waitcnt lgkmcnt(0)
	s_barrier
	s_cmp_lg_u32 s5, 0
	s_cbranch_scc1 .LBB0_24
	ds_read_b32 v34, v33
	ds_read_b32 v35, v33 offset:1024
	ds_read_b32 v36, v33 offset:2048
	ds_read_b32 v37, v33 offset:3072
	ds_read_b32 v38, v33 offset:4096
	s_mul_i32 s8, s4, 0x1e000
	s_lshl_b32 s9, s6, 8
	s_add_u32 s8, s8, s9
	s_add_u32 s8, s8, 0x1410000
	s_add_u32 s28, s24, s8
	s_addc_u32 s29, s25, 0
	s_waitcnt lgkmcnt(0)
	v_add_f32_e32 v10, v10, v34
	v_add_f32_e32 v11, v11, v35
	v_add_f32_e32 v8, v8, v36
	v_add_f32_e32 v9, v9, v37
	v_add_f32_e32 v22, v22, v38
	global_store_dword v27, v10, s[28:29]
	s_add_u32 s28, s28, 0x3000
	s_addc_u32 s29, s29, 0
	global_store_dword v27, v11, s[28:29]
	s_add_u32 s28, s28, 0x3000
	s_addc_u32 s29, s29, 0
	global_store_dword v27, v8, s[28:29]
	s_add_u32 s28, s28, 0x3000
	s_addc_u32 s29, s29, 0
	global_store_dword v27, v9, s[28:29]
	s_add_u32 s28, s28, 0x3000
	s_addc_u32 s29, s29, 0
	global_store_dword v27, v22, s[28:29]
	s_branch .LBB0_24
.Lmp_orig:
	v_bfe_u32 v5, v16, 6, 3
	v_and_b32_e32 v4, 63, v0
	v_mul_u32_u24_e32 v0, 0x7800, v5
	v_lshlrev_b32_e32 v0, 2, v0
	v_mov_b32_e32 v1, 0
	v_lshl_add_u64 v[2:3], s[24:25], 0, v[0:1]
	v_mul_u32_u24_e32 v8, 0x60000, v5
	v_lshlrev_b32_e32 v0, 2, v4
	v_lshl_add_u64 v[2:3], v[2:3], 0, v[0:1]
	v_lshl_or_b32 v0, v8, 2, v0
	v_mbcnt_hi_u32_b32 v7, -1, v225
	v_lshl_or_b32 v18, v5, 7, v4
	s_mov_b64 s[4:5], 0x1410000
	s_waitcnt lgkmcnt(0)
	v_lshl_add_u64 v[4:5], s[52:53], 0, v[0:1]
	v_lshlrev_b32_e32 v0, 3, v6
	v_lshl_add_u64 v[2:3], v[2:3], 0, s[4:5]
	v_lshl_add_u32 v19, s2, 6, v0
	v_lshlrev_b32_e32 v0, 2, v7
	s_movk_i32 s4, 0x100
	s_lshl_b32 s3, s26, 6
	v_and_or_b32 v20, v0, s4, 60
	s_mov_b64 s[4:5], 0
	s_movk_i32 s10, 0x2000
	s_movk_i32 s11, 0x3000
	v_mov_b32_e32 v21, 0x3000
	s_movk_i32 s12, 0x6000
	s_mov_b32 s13, 0x9000
	s_mov_b32 s14, 0xc000
	s_mov_b32 s15, 0xf000
	s_mov_b32 s16, 0x12000
	s_mov_b32 s17, 0x15000
	s_mov_b32 s19, 0x18000
	s_mov_b32 s28, 0x1b000
	s_mov_b32 s29, 0x1e000
	s_mov_b32 s30, 0x21000
	s_mov_b32 s31, 0x24000
	s_mov_b32 s34, 0x27000
	s_mov_b32 s35, 0x2a000
	s_mov_b32 s68, 0x2d000
	s_movk_i32 s69, 0x17f

.LBB0_27:
	s_or_b64 exec, exec, s[4:5]
	s_cmpk_lg_i32 s26, 0x100
	s_cselect_b64 s[0:1], -1, 0
	s_sub_i32 s3, s2, 0x60
	v_writelane_b32 v254, s0, 19
	s_cmpk_eq_i32 s26, 0x100
	s_nop 0
	v_writelane_b32 v254, s1, 20
	s_cselect_b64 s[0:1], -1, 0
	v_writelane_b32 v254, s0, 11
	s_nop 1
	v_writelane_b32 v254, s1, 12
	s_and_b64 s[0:1], s[0:1], exec
	s_cselect_b32 s0, s3, s2
	s_cmpk_lt_u32 s0, 0x208
	s_cbranch_scc0 .LBB0_42
	v_readlane_b32 s4, v254, 11
	s_lshl_b32 s3, s0, 1
	s_lshl_b32 s1, s26, 1
	v_readlane_b32 s5, v254, 12
	s_and_b64 s[4:5], s[4:5], exec
	s_cselect_b32 s6, 0x140, s1
	s_lshl_b32 s7, s0, 7
	s_lshl_b32 s8, s6, 6
	v_mov_b32_e32 v17, 0
	s_movk_i32 s9, 0x1020
	s_movk_i32 s10, 0x4080
	s_movk_i32 s11, 0x104
	s_branch .LBB0_30
